# P5 act/side stores write-through (sc1) so the grid barrier release has less dirty L2 to flush
# speedup vs baseline: 1.0647x; 1.0004x over previous
.LBB0_154:
	v_mov_b32_e32 v131, v196
	v_mov_b32_e32 v133, v196
	v_lshl_add_u64 v[6:7], s[44:45], 0, v[130:131]
	v_lshl_add_u64 v[8:9], s[44:45], 0, v[132:133]
	v_lshl_add_u64 v[4:5], s[0:1], 0, v[130:131]
	v_lshl_add_u64 v[2:3], s[0:1], 0, v[132:133]
	s_and_b64 vcc, exec, s[68:69]
	s_cbranch_vccz .LBB0_160
	v_mov_b32 v17, v0
	s_lshl_b32 s68, s76, 8
	v_ashrrev_i32_e32 v28, 4, v17
	v_lshlrev_b32_e32 v17, 3, v17
	v_and_b32_e32 v17, 0x78, v17
	v_lshl_or_b32 v22, s74, 7, v17
	v_lshl_add_u32 v29, v28, 3, s68
	v_ashrrev_i32_e32 v23, 31, v22
	v_or_b32_e32 v26, 4, v29
	v_mov_b64_e32 v[24:25], s[60:61]
	s_movk_i32 s70, 0x1600
	v_mad_i64_i32 v[26:27], s[68:69], v26, s70, v[24:25]
	v_lshlrev_b64 v[22:23], 1, v[22:23]
	v_lshl_add_u64 v[26:27], v[26:27], 0, v[22:23]
	global_store_dwordx4 v[26:27], v[34:37], off sc1
	v_or_b32_e32 v26, 5, v29
	v_mad_i64_i32 v[26:27], s[68:69], v26, s70, v[24:25]
	v_lshl_add_u64 v[26:27], v[26:27], 0, v[22:23]
	global_store_dwordx4 v[26:27], v[46:49], off sc1
	v_or_b32_e32 v26, 6, v29
	v_mad_i64_i32 v[26:27], s[68:69], v26, s70, v[24:25]
	v_lshl_add_u64 v[26:27], v[26:27], 0, v[22:23]
	global_store_dwordx4 v[26:27], v[58:61], off sc1
	v_or_b32_e32 v26, 7, v29
	v_mad_i64_i32 v[24:25], s[68:69], v26, s70, v[24:25]
	v_lshl_add_u64 v[22:23], v[24:25], 0, v[22:23]
	v_cmp_eq_u32_e32 vcc, 31, v28
	global_store_dwordx4 v[22:23], v[18:21], off sc1
	s_and_saveexec_b64 s[68:69], vcc
	s_cbranch_execz .LBB0_157
	s_lshl_b32 s70, s74, 8
	s_mul_i32 s74, s76, 0xb000
	s_ashr_i32 s71, s70, 31
	s_ashr_i32 s76, s74, 31
	s_add_u32 s74, s58, s74
	s_addc_u32 s76, s59, s76
	s_lshl_b64 s[70:71], s[70:71], 1
	s_add_u32 s70, s74, s70
	v_lshlrev_b32_e32 v18, 1, v17
	v_mov_b32_e32 v19, v196
	s_addc_u32 s71, s76, s71
	v_lshl_add_u64 v[18:19], s[70:71], 0, v[18:19]
	s_mov_b64 s[70:71], 0x5800
	v_add_co_u32_e32 v22, vcc, 0x5000, v18
	v_lshl_add_u64 v[20:21], v[18:19], 0, s[70:71]
	s_nop 0
	v_addc_co_u32_e32 v23, vcc, 0, v19, vcc
	s_mov_b64 s[70:71], 0x8400
	global_store_dwordx4 v[22:23], v[42:45], off offset:2048 sc1
	global_store_dwordx4 v[20:21], v[38:41], off offset:256 sc1
	v_lshl_add_u64 v[20:21], v[18:19], 0, s[70:71]
	v_add_co_u32_e32 v18, vcc, 0x8000, v18
	s_nop 1
	v_addc_co_u32_e32 v19, vcc, 0, v19, vcc
	global_store_dwordx4 v[18:19], v[54:57], off offset:1024 sc1
	global_store_dwordx4 v[20:21], v[50:53], off offset:256 sc1

.LBB0_168:
	s_or_b64 exec, exec, s[0:1]
	v_add_u32_e32 v66, 0, v66
	v_add_u32_e32 v122, v66, v80
	ds_read_b128 v[66:69], v122
	ds_read_b128 v[70:73], v122 offset:256
	v_mul_f32_e32 v114, v22, v128
	v_fmac_f32_e32 v114, v18, v111
	v_lshlrev_b32_e32 v100, 3, v86
	s_waitcnt lgkmcnt(1)
	v_lshlrev_b32_e32 v115, 16, v66
	v_fmac_f32_e32 v114, v26, v115
	v_add_f32_e32 v111, v30, v114
	v_mul_f32_e32 v114, v23, v127
	v_and_b32_e32 v107, 0xffff0000, v66
	v_fmac_f32_e32 v114, v19, v74
	v_fmac_f32_e32 v114, v27, v107
	v_add_f32_e32 v74, v31, v114
	v_mul_f32_e32 v114, v34, v130
	s_waitcnt lgkmcnt(0)
	v_lshlrev_b32_e32 v106, 16, v70
	v_fmac_f32_e32 v114, v62, v113
	v_fmac_f32_e32 v114, v38, v106
	v_add_f32_e32 v113, v42, v114
	v_mul_f32_e32 v114, v35, v129
	v_and_b32_e32 v99, 0xffff0000, v70
	v_fmac_f32_e32 v114, v63, v112
	v_fmac_f32_e32 v114, v39, v99
	v_add_f32_e32 v112, v43, v114
	v_mul_f32_e32 v114, 0xbfb8aa3b, v111
	v_exp_f32_e32 v114, v114
	v_lshlrev_b32_e32 v98, 16, v67
	v_and_b32_e32 v97, 0xffff0000, v67
	v_lshlrev_b32_e32 v96, 16, v71
	v_add_f32_e32 v114, 1.0, v114
	v_rcp_f32_e32 v114, v114
	v_and_b32_e32 v95, 0xffff0000, v71
	v_lshlrev_b32_e32 v94, 16, v68
	v_and_b32_e32 v93, 0xffff0000, v68
	v_mul_f32_e32 v111, v111, v114
	v_mul_f32_e32 v111, v113, v111
	v_mul_f32_e32 v113, 0xbfb8aa3b, v74
	v_exp_f32_e32 v113, v113
	v_lshlrev_b32_e32 v92, 16, v72
	v_and_b32_e32 v91, 0xffff0000, v72
	v_lshlrev_b32_e32 v90, 16, v69
	v_add_f32_e32 v113, 1.0, v113
	v_rcp_f32_e32 v113, v113
	v_and_b32_e32 v89, 0xffff0000, v69
	v_lshlrev_b32_e32 v88, 16, v73
	v_and_b32_e32 v87, 0xffff0000, v73
	v_mul_f32_e32 v74, v74, v113
	v_mul_f32_e32 v74, v112, v74
	v_cvt_pk_bf16_f32 v74, v111, v74
	v_mul_f32_e32 v111, v24, v124
	v_fmac_f32_e32 v111, v20, v108
	v_fmac_f32_e32 v111, v28, v98
	v_add_f32_e32 v108, v32, v111
	v_mul_f32_e32 v111, v25, v123
	v_fmac_f32_e32 v111, v21, v75
	v_fmac_f32_e32 v111, v29, v97
	v_add_f32_e32 v75, v33, v111
	v_mul_f32_e32 v111, v36, v126
	v_fmac_f32_e32 v111, v64, v110
	v_fmac_f32_e32 v111, v40, v96
	v_add_f32_e32 v110, v44, v111
	v_mul_f32_e32 v111, v37, v125
	v_fmac_f32_e32 v111, v65, v109
	v_fmac_f32_e32 v111, v41, v95
	v_add_f32_e32 v109, v45, v111
	v_mul_f32_e32 v111, 0xbfb8aa3b, v108
	v_exp_f32_e32 v111, v111
	s_lshl_b32 s37, s36, 8
	v_add_f32_e32 v111, 1.0, v111
	v_rcp_f32_e32 v111, v111
	s_nop 0
	v_mul_f32_e32 v108, v108, v111
	v_mul_f32_e32 v108, v110, v108
	v_mul_f32_e32 v110, 0xbfb8aa3b, v75
	v_exp_f32_e32 v110, v110
	s_nop 0
	v_add_f32_e32 v110, 1.0, v110
	v_rcp_f32_e32 v110, v110
	s_nop 0
	v_mul_f32_e32 v75, v75, v110
	v_mul_f32_e32 v75, v109, v75
	v_cvt_pk_bf16_f32 v75, v108, v75
	v_mul_f32_e32 v108, v6, v85
	v_fmac_f32_e32 v108, v2, v103
	v_fmac_f32_e32 v108, v10, v94
	v_add_f32_e32 v103, v14, v108
	v_mul_f32_e32 v108, v7, v84
	v_fmac_f32_e32 v108, v3, v76
	v_fmac_f32_e32 v108, v11, v93
	v_add_f32_e32 v76, v15, v108
	v_mul_f32_e32 v108, v46, v121
	v_fmac_f32_e32 v108, v58, v105
	v_fmac_f32_e32 v108, v50, v92
	v_add_f32_e32 v105, v54, v108
	v_mul_f32_e32 v108, v47, v120
	v_fmac_f32_e32 v108, v59, v104
	v_fmac_f32_e32 v108, v51, v91
	v_add_f32_e32 v104, v55, v108
	v_mul_f32_e32 v108, 0xbfb8aa3b, v103
	v_exp_f32_e32 v108, v108
	s_nop 0
	v_add_f32_e32 v108, 1.0, v108
	v_rcp_f32_e32 v108, v108
	s_nop 0
	v_mul_f32_e32 v103, v103, v108
	v_mul_f32_e32 v103, v105, v103
	v_mul_f32_e32 v105, 0xbfb8aa3b, v76
	v_exp_f32_e32 v105, v105
	s_nop 0
	v_add_f32_e32 v105, 1.0, v105
	v_rcp_f32_e32 v105, v105
	s_nop 0
	v_mul_f32_e32 v76, v76, v105
	v_mul_f32_e32 v76, v104, v76
	v_cvt_pk_bf16_f32 v76, v103, v76
	v_mul_f32_e32 v103, v8, v81
	v_fmac_f32_e32 v103, v4, v78
	v_fmac_f32_e32 v103, v12, v90
	v_add_f32_e32 v78, v16, v103
	v_mul_f32_e32 v103, v9, v79
	v_fmac_f32_e32 v103, v5, v77
	v_fmac_f32_e32 v103, v13, v89
	v_add_f32_e32 v77, v17, v103
	v_mul_f32_e32 v103, v48, v83
	v_fmac_f32_e32 v103, v60, v102
	v_fmac_f32_e32 v103, v52, v88
	v_add_f32_e32 v102, v56, v103
	v_mul_f32_e32 v103, v49, v82
	v_fmac_f32_e32 v103, v61, v101
	v_fmac_f32_e32 v103, v53, v87
	v_add_f32_e32 v101, v57, v103
	v_mul_f32_e32 v103, 0xbfb8aa3b, v78
	v_exp_f32_e32 v103, v103
	s_nop 0
	v_add_f32_e32 v103, 1.0, v103
	v_rcp_f32_e32 v103, v103
	s_nop 0
	v_mul_f32_e32 v78, v78, v103
	v_mul_f32_e32 v78, v102, v78
	v_mul_f32_e32 v102, 0xbfb8aa3b, v77
	v_exp_f32_e32 v102, v102
	s_nop 0
	v_add_f32_e32 v102, 1.0, v102
	v_rcp_f32_e32 v102, v102
	s_nop 0
	v_mul_f32_e32 v77, v77, v102
	v_mul_f32_e32 v77, v101, v77
	v_cvt_pk_bf16_f32 v77, v78, v77
	s_and_saveexec_b64 s[0:1], vcc
	s_cbranch_execz .LBB0_170
	v_add_u32_e32 v78, s37, v100
	v_mov_b64_e32 v[102:103], s[60:61]
	s_movk_i32 s16, 0x1600
	v_mad_i64_i32 v[102:103], s[16:17], v78, s16, v[102:103]
	v_lshl_add_u64 v[102:103], v[194:195], 1, v[102:103]
	global_store_dwordx4 v[102:103], v[74:77], off sc1
.LBB0_170:
	s_or_b64 exec, exec, s[0:1]
	s_lshl_b32 s16, s42, 8
	v_cmp_gt_u32_e64 s[0:1], 16, v198
	s_ashr_i32 s17, s16, 31
	s_mul_hi_i32 s43, s36, 0xb000
	s_mul_i32 s44, s36, 0xb000
	v_lshlrev_b32_e32 v78, 1, v197
	s_and_saveexec_b64 s[40:41], s[0:1]
	s_cbranch_execz .LBB0_172
	s_add_u32 s45, s58, s44
	s_addc_u32 s70, s59, s43
	s_lshl_b64 s[68:69], s[16:17], 1
	s_add_u32 s68, s45, s68
	s_addc_u32 s69, s70, s69
	global_store_dwordx4 v78, v[66:69], s[68:69] sc1
	global_store_dwordx4 v78, v[70:73], s[68:69] offset:256 sc1
.LBB0_172:
	s_or_b64 exec, exec, s[40:41]
	v_or_b32_e32 v132, 1, v100
	s_movk_i32 s40, 0x210
	v_mul_lo_u32 v66, v132, s40
	v_add_u32_e32 v131, 0, v66
	v_add_u32_e32 v70, v131, v80
	ds_read_b128 v[66:69], v70
	ds_read_b128 v[70:73], v70 offset:256
	v_mul_f32_e32 v74, v22, v115
	v_fmac_f32_e32 v74, v18, v128
	v_mul_f32_e32 v75, v23, v107
	s_waitcnt lgkmcnt(1)
	v_lshlrev_b32_e32 v119, 16, v66
	v_fmac_f32_e32 v74, v26, v119
	v_add_f32_e32 v74, v30, v74
	v_fmac_f32_e32 v75, v19, v127
	v_mul_f32_e32 v127, 0xbfb8aa3b, v74
	v_exp_f32_e32 v127, v127
	v_mul_f32_e32 v76, v34, v106
	v_and_b32_e32 v118, 0xffff0000, v66
	s_waitcnt lgkmcnt(0)
	v_lshlrev_b32_e32 v117, 16, v70
	v_add_f32_e32 v127, 1.0, v127
	v_rcp_f32_e32 v127, v127
	v_fmac_f32_e32 v76, v62, v130
	v_fmac_f32_e32 v75, v27, v118
	v_fmac_f32_e32 v76, v38, v117
	v_add_f32_e32 v75, v31, v75
	v_add_f32_e32 v76, v42, v76
	v_mul_f32_e32 v74, v74, v127
	v_mul_f32_e32 v74, v76, v74
	v_mul_f32_e32 v76, 0xbfb8aa3b, v75
	v_exp_f32_e32 v76, v76
	v_mul_f32_e32 v77, v35, v99
	v_and_b32_e32 v116, 0xffff0000, v70
	v_fmac_f32_e32 v77, v63, v129
	v_add_f32_e32 v76, 1.0, v76
	v_rcp_f32_e32 v76, v76
	v_fmac_f32_e32 v77, v39, v116
	v_add_f32_e32 v77, v43, v77
	v_lshlrev_b32_e32 v114, 16, v67
	v_mul_f32_e32 v75, v75, v76
	v_mul_f32_e32 v75, v77, v75
	v_cvt_pk_bf16_f32 v74, v74, v75
	v_mul_f32_e32 v75, v24, v98
	v_fmac_f32_e32 v75, v20, v124
	v_fmac_f32_e32 v75, v28, v114
	v_add_f32_e32 v75, v32, v75
	v_mul_f32_e32 v124, 0xbfb8aa3b, v75
	v_exp_f32_e32 v124, v124
	v_mul_f32_e32 v76, v25, v97
	v_mul_f32_e32 v77, v36, v96
	v_and_b32_e32 v113, 0xffff0000, v67
	v_add_f32_e32 v124, 1.0, v124
	v_rcp_f32_e32 v124, v124
	v_lshlrev_b32_e32 v112, 16, v71
	v_fmac_f32_e32 v76, v21, v123
	v_fmac_f32_e32 v77, v64, v126
	v_fmac_f32_e32 v76, v29, v113
	v_fmac_f32_e32 v77, v40, v112
	v_add_f32_e32 v76, v33, v76
	v_add_f32_e32 v77, v44, v77
	v_mul_f32_e32 v75, v75, v124
	v_mul_f32_e32 v75, v77, v75
	v_mul_f32_e32 v77, 0xbfb8aa3b, v76
	v_exp_f32_e32 v77, v77
	v_mul_f32_e32 v123, v37, v95
	v_and_b32_e32 v111, 0xffff0000, v71
	v_fmac_f32_e32 v123, v65, v125
	v_add_f32_e32 v77, 1.0, v77
	v_rcp_f32_e32 v77, v77
	v_fmac_f32_e32 v123, v41, v111
	v_add_f32_e32 v123, v45, v123
	v_lshlrev_b32_e32 v110, 16, v68
	v_mul_f32_e32 v76, v76, v77
	v_mul_f32_e32 v76, v123, v76
	v_cvt_pk_bf16_f32 v75, v75, v76
	v_mul_f32_e32 v76, v6, v94
	v_fmac_f32_e32 v76, v2, v85
	v_fmac_f32_e32 v76, v10, v110
	v_add_f32_e32 v76, v14, v76
	v_mul_f32_e32 v85, v47, v91
	v_fmac_f32_e32 v85, v59, v120
	v_mul_f32_e32 v120, 0xbfb8aa3b, v76
	v_exp_f32_e32 v120, v120
	v_mul_f32_e32 v77, v7, v93
	v_fmac_f32_e32 v77, v3, v84
	v_mul_f32_e32 v84, v46, v92
	v_add_f32_e32 v120, 1.0, v120
	v_rcp_f32_e32 v120, v120
	v_and_b32_e32 v109, 0xffff0000, v68
	v_lshlrev_b32_e32 v108, 16, v72
	v_fmac_f32_e32 v84, v58, v121
	v_fmac_f32_e32 v77, v11, v109
	v_fmac_f32_e32 v84, v50, v108
	v_add_f32_e32 v77, v15, v77
	v_add_f32_e32 v84, v54, v84
	v_mul_f32_e32 v76, v76, v120
	v_mul_f32_e32 v76, v84, v76
	v_mul_f32_e32 v84, 0xbfb8aa3b, v77
	v_exp_f32_e32 v84, v84
	v_and_b32_e32 v105, 0xffff0000, v72
	v_fmac_f32_e32 v85, v51, v105
	v_add_f32_e32 v85, v55, v85
	v_add_f32_e32 v84, 1.0, v84
	v_rcp_f32_e32 v84, v84
	v_and_b32_e32 v103, 0xffff0000, v69
	v_lshlrev_b32_e32 v104, 16, v69
	v_and_b32_e32 v101, 0xffff0000, v73
	v_mul_f32_e32 v77, v77, v84
	v_mul_f32_e32 v77, v85, v77
	v_cvt_pk_bf16_f32 v76, v76, v77
	v_mul_f32_e32 v77, v8, v90
	v_fmac_f32_e32 v77, v4, v81
	v_mul_f32_e32 v81, v9, v89
	v_fmac_f32_e32 v81, v5, v79
	v_fmac_f32_e32 v81, v13, v103
	v_add_f32_e32 v79, v17, v81
	v_mul_f32_e32 v81, v48, v88
	v_fmac_f32_e32 v81, v60, v83
	v_mul_f32_e32 v83, v49, v87
	v_fmac_f32_e32 v77, v12, v104
	v_fmac_f32_e32 v83, v61, v82
	v_add_f32_e32 v77, v16, v77
	v_fmac_f32_e32 v83, v53, v101
	v_add_f32_e32 v82, v57, v83
	v_mul_f32_e32 v83, 0xbfb8aa3b, v77
	v_exp_f32_e32 v83, v83
	v_lshlrev_b32_e32 v102, 16, v73
	v_fmac_f32_e32 v81, v52, v102
	v_add_f32_e32 v81, v56, v81
	v_add_f32_e32 v83, 1.0, v83
	v_rcp_f32_e32 v83, v83
	s_nop 0
	v_mul_f32_e32 v77, v77, v83
	v_mul_f32_e32 v77, v81, v77
	v_mul_f32_e32 v81, 0xbfb8aa3b, v79
	v_exp_f32_e32 v81, v81
	s_nop 0
	v_add_f32_e32 v81, 1.0, v81
	v_rcp_f32_e32 v81, v81
	s_nop 0
	v_mul_f32_e32 v79, v79, v81
	v_mul_f32_e32 v79, v82, v79
	v_cvt_pk_bf16_f32 v77, v77, v79
	s_and_saveexec_b64 s[40:41], vcc
	s_cbranch_execz .LBB0_174
	v_add_u32_e32 v79, s37, v132
	v_mov_b64_e32 v[82:83], s[60:61]
	s_movk_i32 s45, 0x1600
	v_mad_i64_i32 v[82:83], s[68:69], v79, s45, v[82:83]
	v_lshl_add_u64 v[82:83], v[194:195], 1, v[82:83]
	global_store_dwordx4 v[82:83], v[74:77], off sc1
.LBB0_174:
	s_or_b64 exec, exec, s[40:41]
	s_and_saveexec_b64 s[40:41], s[0:1]
	s_cbranch_execz .LBB0_176
	s_add_u32 s44, s58, s44
	s_addc_u32 s43, s59, s43
	s_lshl_b64 s[0:1], s[16:17], 1
	s_add_u32 s0, s44, s0
	s_addc_u32 s1, s43, s1
	v_mov_b32_e32 v79, v196
	v_lshl_add_u64 v[74:75], s[0:1], 0, v[78:79]
	s_mov_b64 s[0:1], 0x2c00
	v_lshl_add_u64 v[76:77], v[74:75], 0, s[0:1]
	v_add_co_u32_e32 v74, vcc, 0x2000, v74
	s_nop 1
	v_addc_co_u32_e32 v75, vcc, 0, v75, vcc
	global_store_dwordx4 v[74:75], v[66:69], off offset:3072 sc1
	global_store_dwordx4 v[76:77], v[70:73], off offset:256 sc1
.LBB0_176:
	s_or_b64 exec, exec, s[40:41]
	v_add_u32_e32 v66, 0x210, v131
	v_add_u32_e32 v120, v66, v80
	ds_read_b128 v[66:69], v120
	ds_read_b128 v[124:127], v120 offset:256
	v_cmp_lt_i32_e32 vcc, -1, v86
	s_waitcnt lgkmcnt(1)
	v_lshlrev_b32_e32 v73, 16, v66
	v_and_b32_e32 v71, 0xffff0000, v66
	v_mul_f32_e32 v66, v22, v119
	v_fmac_f32_e32 v66, v18, v115
	v_fmac_f32_e32 v66, v26, v73
	v_lshlrev_b32_e32 v85, 16, v69
	v_and_b32_e32 v83, 0xffff0000, v69
	v_add_f32_e32 v66, v30, v66
	v_mul_f32_e32 v69, v35, v116
	v_fmac_f32_e32 v69, v63, v99
	v_mul_f32_e32 v99, 0xbfb8aa3b, v66
	v_exp_f32_e32 v99, v99
	v_lshlrev_b32_e32 v77, 16, v67
	v_and_b32_e32 v75, 0xffff0000, v67
	v_lshlrev_b32_e32 v81, 16, v68
	v_add_f32_e32 v99, 1.0, v99
	v_rcp_f32_e32 v99, v99
	v_and_b32_e32 v79, 0xffff0000, v68
	v_mul_f32_e32 v67, v23, v118
	v_mul_f32_e32 v68, v34, v117
	s_waitcnt lgkmcnt(0)
	v_lshlrev_b32_e32 v72, 16, v124
	v_fmac_f32_e32 v67, v19, v107
	v_fmac_f32_e32 v68, v62, v106
	v_fmac_f32_e32 v67, v27, v71
	v_fmac_f32_e32 v68, v38, v72
	v_add_f32_e32 v67, v31, v67
	v_add_f32_e32 v68, v42, v68
	v_mul_f32_e32 v66, v66, v99
	v_mul_f32_e32 v66, v68, v66
	v_mul_f32_e32 v68, 0xbfb8aa3b, v67
	v_exp_f32_e32 v68, v68
	v_and_b32_e32 v70, 0xffff0000, v124
	v_fmac_f32_e32 v69, v39, v70
	v_add_f32_e32 v69, v43, v69
	v_add_f32_e32 v68, 1.0, v68
	v_rcp_f32_e32 v68, v68
	v_and_b32_e32 v74, 0xffff0000, v125
	v_lshlrev_b32_e32 v76, 16, v125
	v_lshlrev_b32_e32 v80, 16, v126
	v_mul_f32_e32 v67, v67, v68
	v_mul_f32_e32 v67, v69, v67
	v_cvt_pk_bf16_f32 v66, v66, v67
	v_mul_f32_e32 v67, v24, v114
	v_mul_f32_e32 v69, v36, v112
	v_fmac_f32_e32 v67, v20, v98
	v_fmac_f32_e32 v69, v64, v96
	v_mul_f32_e32 v96, v37, v111
	v_fmac_f32_e32 v67, v28, v77
	v_fmac_f32_e32 v96, v65, v95
	v_add_f32_e32 v67, v32, v67
	v_fmac_f32_e32 v96, v41, v74
	v_add_f32_e32 v95, v45, v96
	v_mul_f32_e32 v96, 0xbfb8aa3b, v67
	v_exp_f32_e32 v96, v96
	v_mul_f32_e32 v68, v25, v113
	v_fmac_f32_e32 v68, v21, v97
	v_fmac_f32_e32 v68, v29, v75
	v_add_f32_e32 v96, 1.0, v96
	v_rcp_f32_e32 v96, v96
	v_fmac_f32_e32 v69, v40, v76
	v_add_f32_e32 v68, v33, v68
	v_add_f32_e32 v69, v44, v69
	v_mul_f32_e32 v67, v67, v96
	v_mul_f32_e32 v67, v69, v67
	v_mul_f32_e32 v69, 0xbfb8aa3b, v68
	v_exp_f32_e32 v69, v69
	v_and_b32_e32 v78, 0xffff0000, v126
	v_lshlrev_b32_e32 v84, 16, v127
	v_and_b32_e32 v82, 0xffff0000, v127
	v_add_f32_e32 v69, 1.0, v69
	v_rcp_f32_e32 v69, v69
	s_nop 0
	v_mul_f32_e32 v68, v68, v69
	v_mul_f32_e32 v69, v7, v109
	v_fmac_f32_e32 v69, v3, v93
	v_mul_f32_e32 v93, v46, v108
	v_mul_f32_e32 v68, v95, v68
	v_fmac_f32_e32 v93, v58, v92
	v_cvt_pk_bf16_f32 v67, v67, v68
	v_mul_f32_e32 v68, v6, v110
	v_fmac_f32_e32 v93, v50, v80
	v_fmac_f32_e32 v68, v2, v94
	v_add_f32_e32 v92, v54, v93
	v_mul_f32_e32 v93, v47, v105
	v_fmac_f32_e32 v68, v10, v81
	v_fmac_f32_e32 v93, v59, v91
	v_add_f32_e32 v68, v14, v68
	v_fmac_f32_e32 v93, v51, v78
	v_add_f32_e32 v91, v55, v93
	v_mul_f32_e32 v93, 0xbfb8aa3b, v68
	v_exp_f32_e32 v93, v93
	v_fmac_f32_e32 v69, v11, v79
	v_add_f32_e32 v69, v15, v69
	v_add_f32_e32 v93, 1.0, v93
	v_rcp_f32_e32 v93, v93
	s_nop 0
	v_mul_f32_e32 v68, v68, v93
	v_mul_f32_e32 v68, v92, v68
	v_mul_f32_e32 v92, 0xbfb8aa3b, v69
	v_exp_f32_e32 v92, v92
	s_nop 0
	v_add_f32_e32 v92, 1.0, v92
	v_rcp_f32_e32 v92, v92
	s_nop 0
	v_mul_f32_e32 v69, v69, v92
	v_mul_f32_e32 v69, v91, v69
	v_cvt_pk_bf16_f32 v68, v68, v69
	v_mul_f32_e32 v69, v8, v104
	v_fmac_f32_e32 v69, v4, v90
	v_mul_f32_e32 v90, v9, v103
	v_fmac_f32_e32 v90, v5, v89
	v_fmac_f32_e32 v90, v13, v83
	v_add_f32_e32 v89, v17, v90
	v_mul_f32_e32 v90, v48, v102
	v_fmac_f32_e32 v90, v60, v88
	v_fmac_f32_e32 v90, v52, v84
	v_add_f32_e32 v88, v56, v90
	v_mul_f32_e32 v90, v49, v101
	v_fmac_f32_e32 v69, v12, v85
	v_fmac_f32_e32 v90, v61, v87
	v_add_f32_e32 v69, v16, v69
	v_fmac_f32_e32 v90, v53, v82
	v_add_f32_e32 v87, v57, v90
	v_mul_f32_e32 v90, 0xbfb8aa3b, v69
	v_exp_f32_e32 v90, v90
	s_nop 0
	v_add_f32_e32 v90, 1.0, v90
	v_rcp_f32_e32 v90, v90
	s_nop 0
	v_mul_f32_e32 v69, v69, v90
	v_mul_f32_e32 v69, v88, v69
	v_mul_f32_e32 v88, 0xbfb8aa3b, v89
	v_exp_f32_e32 v88, v88
	s_nop 0
	v_add_f32_e32 v88, 1.0, v88
	v_rcp_f32_e32 v88, v88
	s_nop 0
	v_mul_f32_e32 v88, v89, v88
	v_mul_f32_e32 v87, v87, v88
	v_cvt_pk_bf16_f32 v69, v69, v87
	s_and_saveexec_b64 s[0:1], vcc
	s_cbranch_execz .LBB0_178
	v_add3_u32 v88, s37, v100, 2
	v_mov_b64_e32 v[86:87], s[60:61]
	s_movk_i32 s40, 0x1600
	v_mad_i64_i32 v[86:87], s[40:41], v88, s40, v[86:87]
	v_lshl_add_u64 v[86:87], v[194:195], 1, v[86:87]
	global_store_dwordx4 v[86:87], v[66:69], off sc1
.LBB0_178:
	s_or_b64 exec, exec, s[0:1]
	ds_read_b128 v[66:69], v120 offset:528
	ds_read_b128 v[124:127], v120 offset:784
	s_waitcnt lgkmcnt(1)
	v_lshlrev_b32_e32 v89, 16, v66
	v_and_b32_e32 v87, 0xffff0000, v66
	v_mul_f32_e32 v66, v22, v73
	v_fmac_f32_e32 v66, v18, v119
	v_fmac_f32_e32 v66, v26, v89
	v_add_f32_e32 v66, v30, v66
	v_mul_f32_e32 v115, 0xbfb8aa3b, v66
	v_exp_f32_e32 v115, v115
	v_lshlrev_b32_e32 v93, 16, v67
	v_and_b32_e32 v91, 0xffff0000, v67
	v_lshlrev_b32_e32 v97, 16, v68
	v_add_f32_e32 v115, 1.0, v115
	v_rcp_f32_e32 v115, v115
	v_and_b32_e32 v95, 0xffff0000, v68
	v_mul_f32_e32 v67, v23, v71
	v_mul_f32_e32 v68, v34, v72
	s_waitcnt lgkmcnt(0)
	v_lshlrev_b32_e32 v88, 16, v124
	v_fmac_f32_e32 v67, v19, v118
	v_fmac_f32_e32 v68, v62, v117
	v_fmac_f32_e32 v67, v27, v87
	v_fmac_f32_e32 v68, v38, v88
	v_add_f32_e32 v67, v31, v67
	v_add_f32_e32 v68, v42, v68
	v_mul_f32_e32 v66, v66, v115
	v_mul_f32_e32 v66, v68, v66
	v_mul_f32_e32 v68, 0xbfb8aa3b, v67
	v_exp_f32_e32 v68, v68
	v_lshlrev_b32_e32 v107, 16, v69
	v_and_b32_e32 v99, 0xffff0000, v69
	v_mul_f32_e32 v69, v35, v70
	v_add_f32_e32 v68, 1.0, v68
	v_rcp_f32_e32 v68, v68
	v_and_b32_e32 v86, 0xffff0000, v124
	v_fmac_f32_e32 v69, v63, v116
	v_fmac_f32_e32 v69, v39, v86
	v_add_f32_e32 v69, v43, v69
	v_mul_f32_e32 v67, v67, v68
	v_mul_f32_e32 v67, v69, v67
	v_cvt_pk_bf16_f32 v66, v66, v67
	v_mul_f32_e32 v67, v24, v77
	v_mul_f32_e32 v69, v36, v76
	v_fmac_f32_e32 v67, v20, v114
	v_fmac_f32_e32 v69, v64, v112
	v_mul_f32_e32 v112, v37, v74
	v_and_b32_e32 v90, 0xffff0000, v125
	v_fmac_f32_e32 v67, v28, v93
	v_fmac_f32_e32 v112, v65, v111
	v_add_f32_e32 v67, v32, v67
	v_fmac_f32_e32 v112, v41, v90
	v_add_f32_e32 v111, v45, v112
	v_mul_f32_e32 v112, 0xbfb8aa3b, v67
	v_exp_f32_e32 v112, v112
	v_mul_f32_e32 v68, v25, v75
	v_lshlrev_b32_e32 v92, 16, v125
	v_fmac_f32_e32 v68, v21, v113
	v_add_f32_e32 v112, 1.0, v112
	v_rcp_f32_e32 v112, v112
	v_fmac_f32_e32 v68, v29, v91
	v_fmac_f32_e32 v69, v40, v92
	v_add_f32_e32 v68, v33, v68
	v_add_f32_e32 v69, v44, v69
	v_mul_f32_e32 v67, v67, v112
	v_mul_f32_e32 v67, v69, v67
	v_mul_f32_e32 v69, 0xbfb8aa3b, v68
	v_exp_f32_e32 v69, v69
	v_lshlrev_b32_e32 v96, 16, v126
	v_and_b32_e32 v94, 0xffff0000, v126
	v_lshlrev_b32_e32 v106, 16, v127
	v_add_f32_e32 v69, 1.0, v69
	v_rcp_f32_e32 v69, v69
	v_and_b32_e32 v98, 0xffff0000, v127
	v_mul_f32_e32 v68, v68, v69
	v_mul_f32_e32 v69, v7, v79
	v_fmac_f32_e32 v69, v3, v109
	v_mul_f32_e32 v109, v46, v80
	v_mul_f32_e32 v68, v111, v68
	v_fmac_f32_e32 v109, v58, v108
	v_cvt_pk_bf16_f32 v67, v67, v68
	v_mul_f32_e32 v68, v6, v81
	v_fmac_f32_e32 v109, v50, v96
	v_fmac_f32_e32 v68, v2, v110
	v_add_f32_e32 v108, v54, v109
	v_mul_f32_e32 v109, v47, v78
	v_fmac_f32_e32 v68, v10, v97
	v_fmac_f32_e32 v109, v59, v105
	v_add_f32_e32 v68, v14, v68
	v_fmac_f32_e32 v109, v51, v94
	v_add_f32_e32 v105, v55, v109
	v_mul_f32_e32 v109, 0xbfb8aa3b, v68
	v_exp_f32_e32 v109, v109
	v_fmac_f32_e32 v69, v11, v95
	v_add_f32_e32 v69, v15, v69
	v_add_f32_e32 v109, 1.0, v109
	v_rcp_f32_e32 v109, v109
	s_nop 0
	v_mul_f32_e32 v68, v68, v109
	v_mul_f32_e32 v68, v108, v68
	v_mul_f32_e32 v108, 0xbfb8aa3b, v69
	v_exp_f32_e32 v108, v108
	s_nop 0
	v_add_f32_e32 v108, 1.0, v108
	v_rcp_f32_e32 v108, v108
	s_nop 0
	v_mul_f32_e32 v69, v69, v108
	v_mul_f32_e32 v69, v105, v69
	v_cvt_pk_bf16_f32 v68, v68, v69
	v_mul_f32_e32 v69, v8, v85
	v_fmac_f32_e32 v69, v4, v104
	v_mul_f32_e32 v104, v9, v83
	v_fmac_f32_e32 v104, v5, v103
	v_fmac_f32_e32 v104, v13, v99
	v_add_f32_e32 v103, v17, v104
	v_mul_f32_e32 v104, v48, v84
	v_fmac_f32_e32 v104, v60, v102
	v_fmac_f32_e32 v104, v52, v106
	v_add_f32_e32 v102, v56, v104
	v_mul_f32_e32 v104, v49, v82
	v_fmac_f32_e32 v69, v12, v107
	v_fmac_f32_e32 v104, v61, v101
	v_add_f32_e32 v69, v16, v69
	v_fmac_f32_e32 v104, v53, v98
	v_add_f32_e32 v101, v57, v104
	v_mul_f32_e32 v104, 0xbfb8aa3b, v69
	v_exp_f32_e32 v104, v104
	s_nop 0
	v_add_f32_e32 v104, 1.0, v104
	v_rcp_f32_e32 v104, v104
	s_nop 0
	v_mul_f32_e32 v69, v69, v104
	v_mul_f32_e32 v69, v102, v69
	v_mul_f32_e32 v102, 0xbfb8aa3b, v103
	v_exp_f32_e32 v102, v102
	s_nop 0
	v_add_f32_e32 v102, 1.0, v102
	v_rcp_f32_e32 v102, v102
	s_nop 0
	v_mul_f32_e32 v102, v103, v102
	v_mul_f32_e32 v101, v101, v102
	v_cvt_pk_bf16_f32 v69, v69, v101
	s_and_saveexec_b64 s[0:1], vcc
	s_cbranch_execz .LBB0_180
	v_add3_u32 v102, s37, v100, 3
	v_mov_b64_e32 v[100:101], s[60:61]
	s_movk_i32 s40, 0x1600
	v_mad_i64_i32 v[100:101], s[40:41], v102, s40, v[100:101]
	v_lshl_add_u64 v[100:101], v[194:195], 1, v[100:101]
	global_store_dwordx4 v[100:101], v[66:69], off sc1

.LBB0_182:
	v_mov_b32 v2, v0
	v_mov_b64_e32 v[6:7], s[60:61]
	v_ashrrev_i32_e32 v3, 4, v2
	v_lshlrev_b32_e32 v2, 3, v2
	v_and_b32_e32 v2, 0x78, v2
	v_or_b32_e32 v4, s33, v2
	v_lshl_add_u32 v10, v3, 3, s37
	v_ashrrev_i32_e32 v5, 31, v4
	v_or_b32_e32 v8, 4, v10
	s_movk_i32 s2, 0x1600
	v_mad_i64_i32 v[8:9], s[0:1], v8, s2, v[6:7]
	v_lshlrev_b64 v[4:5], 1, v[4:5]
	v_lshl_add_u64 v[8:9], v[8:9], 0, v[4:5]
	global_store_dwordx4 v[8:9], v[34:37], off sc1
	v_or_b32_e32 v8, 5, v10
	v_mad_i64_i32 v[8:9], s[0:1], v8, s2, v[6:7]
	v_lshl_add_u64 v[8:9], v[8:9], 0, v[4:5]
	global_store_dwordx4 v[8:9], v[46:49], off sc1
	v_or_b32_e32 v8, 6, v10
	v_mad_i64_i32 v[8:9], s[0:1], v8, s2, v[6:7]
	v_lshl_add_u64 v[8:9], v[8:9], 0, v[4:5]
	global_store_dwordx4 v[8:9], v[58:61], off sc1
	v_or_b32_e32 v8, 7, v10
	v_mad_i64_i32 v[6:7], s[0:1], v8, s2, v[6:7]
	v_lshl_add_u64 v[4:5], v[6:7], 0, v[4:5]
	v_cmp_eq_u32_e32 vcc, 31, v3
	global_store_dwordx4 v[4:5], v[18:21], off sc1
	s_and_saveexec_b64 s[0:1], vcc
	s_mov_b32 s81, 0x8000
	s_mov_b32 s77, 0x7f807f81
	s_movk_i32 s75, 0x410
	s_cbranch_execz .LBB0_184
	s_mul_i32 s2, s36, 0xb000
	s_ashr_i32 s33, s2, 31
	s_add_u32 s2, s58, s2
	s_addc_u32 s33, s59, s33
	s_lshl_b64 s[16:17], s[16:17], 1
	s_add_u32 s16, s2, s16
	v_lshlrev_b32_e32 v2, 1, v2
	v_mov_b32_e32 v3, v196
	s_addc_u32 s17, s33, s17
	v_lshl_add_u64 v[2:3], s[16:17], 0, v[2:3]
	s_mov_b64 s[16:17], 0x5800
	v_add_co_u32_e32 v6, vcc, 0x5000, v2
	v_lshl_add_u64 v[4:5], v[2:3], 0, s[16:17]
	s_nop 0
	v_addc_co_u32_e32 v7, vcc, 0, v3, vcc
	s_mov_b64 s[16:17], 0x8400
	global_store_dwordx4 v[6:7], v[42:45], off offset:2048 sc1
	global_store_dwordx4 v[4:5], v[38:41], off offset:256 sc1
	v_lshl_add_u64 v[4:5], v[2:3], 0, s[16:17]
	v_add_co_u32_e32 v2, vcc, 0x8000, v2
	s_nop 1
	v_addc_co_u32_e32 v3, vcc, 0, v3, vcc
	global_store_dwordx4 v[2:3], v[54:57], off offset:1024 sc1
	global_store_dwordx4 v[4:5], v[50:53], off offset:256 sc1
